# v94 with the vT-path stores delayed one row group so the ds_bpermute latency overlaps the next group's conversion (counted lgkmcnt wait, alternating address registers)
# speedup vs baseline: 1.0011x; 1.0011x over previous
.LBB0_431:
	s_andn2_b64 vcc, exec, s[4:5]
	s_cbranch_vccnz .LBB0_391
	v_or_b32_e32 v0, s7, v199
	s_lshl_b32 s7, s35, 8
	s_cmp_lt_u32 s35, 30
	s_mov_b64 s[4:5], -1
	v_ashrrev_i32_e32 v1, 31, v0
	s_cbranch_scc1 .LBB0_434
	s_waitcnt lgkmcnt(0)
	v_readlane_b32 s4, v252, 15
	v_readlane_b32 s5, v252, 16
	v_and_b32_e32 v2, 3, v220
	v_and_b32_e32 v0, 0xffffffe0, v0
	v_lshl_or_b32 v0, v2, 3, v0
	v_ashrrev_i32_e32 v1, 31, v0
	v_add_u32_e32 v10, s7, v200
	v_and_b32_e32 v8, 15, v220
	v_sub_u32_e32 v10, v10, v8
	v_bfe_u32 v8, v220, 2, 4
	v_add_u32_e32 v10, v10, v8
	v_lshl_or_b32 v9, v2, 4, v8
	v_lshlrev_b32_e32 v9, 2, v9
	v_lshlrev_b64 v[6:7], 1, v[0:1]
	v_mov_b64_e32 v[2:3], s[4:5]
	v_mad_i64_i32 v[4:5], s[4:5], v10, s94, v[2:3]
	v_lshl_add_u64 v[4:5], v[4:5], 0, v[6:7]
	v_cvt_pk_f16_f32 v158, v158, v159
	v_cvt_pk_f16_f32 v159, v160, v161
	v_cvt_pk_f16_f32 v160, v142, v143
	v_cvt_pk_f16_f32 v161, v144, v145
	v_cvt_pk_f16_f32 v94, v94, v95
	v_cvt_pk_f16_f32 v95, v96, v97
	v_cvt_pk_f16_f32 v96, v78, v79
	v_cvt_pk_f16_f32 v97, v80, v81
	v_permlane32_swap_b32_e32 v158, v160
	v_permlane32_swap_b32_e32 v159, v161
	v_permlane32_swap_b32_e32 v94, v96
	v_permlane32_swap_b32_e32 v95, v97
	v_permlane16_swap_b32_e32 v158, v160
	v_permlane16_swap_b32_e32 v159, v161
	v_permlane16_swap_b32_e32 v94, v96
	v_permlane16_swap_b32_e32 v95, v97
	s_nop 1
	ds_bpermute_b32 v158, v9, v158
	ds_bpermute_b32 v159, v9, v159
	ds_bpermute_b32 v160, v9, v160
	ds_bpermute_b32 v161, v9, v161
	ds_bpermute_b32 v94, v9, v94
	ds_bpermute_b32 v95, v9, v95
	ds_bpermute_b32 v96, v9, v96
	ds_bpermute_b32 v97, v9, v97
	v_or_b32_e32 v12, 16, v10
	v_mad_i64_i32 v[12:13], s[4:5], v12, s94, v[2:3]
	v_lshl_add_u64 v[12:13], v[12:13], 0, v[6:7]
	v_cvt_pk_f16_f32 v150, v150, v151
	v_cvt_pk_f16_f32 v151, v152, v153
	v_cvt_pk_f16_f32 v152, v134, v135
	v_cvt_pk_f16_f32 v153, v136, v137
	v_cvt_pk_f16_f32 v86, v86, v87
	v_cvt_pk_f16_f32 v87, v88, v89
	v_cvt_pk_f16_f32 v88, v70, v71
	v_cvt_pk_f16_f32 v89, v72, v73
	v_permlane32_swap_b32_e32 v150, v152
	v_permlane32_swap_b32_e32 v151, v153
	v_permlane32_swap_b32_e32 v86, v88
	v_permlane32_swap_b32_e32 v87, v89
	v_permlane16_swap_b32_e32 v150, v152
	v_permlane16_swap_b32_e32 v151, v153
	v_permlane16_swap_b32_e32 v86, v88
	v_permlane16_swap_b32_e32 v87, v89
	s_nop 1
	ds_bpermute_b32 v150, v9, v150
	ds_bpermute_b32 v151, v9, v151
	ds_bpermute_b32 v152, v9, v152
	ds_bpermute_b32 v153, v9, v153
	ds_bpermute_b32 v86, v9, v86
	ds_bpermute_b32 v87, v9, v87
	ds_bpermute_b32 v88, v9, v88
	ds_bpermute_b32 v89, v9, v89
	s_waitcnt lgkmcnt(8)
	global_store_dwordx4 v[4:5], v[158:161], off
	global_store_dwordx4 v[4:5], v[94:97], off offset:256
	v_or_b32_e32 v4, 32, v10
	v_mad_i64_i32 v[4:5], s[4:5], v4, s94, v[2:3]
	v_lshl_add_u64 v[4:5], v[4:5], 0, v[6:7]
	v_cvt_pk_f16_f32 v154, v154, v155
	v_cvt_pk_f16_f32 v155, v156, v157
	v_cvt_pk_f16_f32 v156, v138, v139
	v_cvt_pk_f16_f32 v157, v140, v141
	v_cvt_pk_f16_f32 v90, v90, v91
	v_cvt_pk_f16_f32 v91, v92, v93
	v_cvt_pk_f16_f32 v92, v74, v75
	v_cvt_pk_f16_f32 v93, v76, v77
	v_permlane32_swap_b32_e32 v154, v156
	v_permlane32_swap_b32_e32 v155, v157
	v_permlane32_swap_b32_e32 v90, v92
	v_permlane32_swap_b32_e32 v91, v93
	v_permlane16_swap_b32_e32 v154, v156
	v_permlane16_swap_b32_e32 v155, v157
	v_permlane16_swap_b32_e32 v90, v92
	v_permlane16_swap_b32_e32 v91, v93
	s_nop 1
	ds_bpermute_b32 v154, v9, v154
	ds_bpermute_b32 v155, v9, v155
	ds_bpermute_b32 v156, v9, v156
	ds_bpermute_b32 v157, v9, v157
	ds_bpermute_b32 v90, v9, v90
	ds_bpermute_b32 v91, v9, v91
	ds_bpermute_b32 v92, v9, v92
	ds_bpermute_b32 v93, v9, v93
	s_waitcnt lgkmcnt(8)
	global_store_dwordx4 v[12:13], v[150:153], off
	global_store_dwordx4 v[12:13], v[86:89], off offset:256
	v_or_b32_e32 v12, 48, v10
	v_mad_i64_i32 v[12:13], s[4:5], v12, s94, v[2:3]
	v_lshl_add_u64 v[12:13], v[12:13], 0, v[6:7]
	v_cvt_pk_f16_f32 v146, v146, v147
	v_cvt_pk_f16_f32 v147, v148, v149
	v_cvt_pk_f16_f32 v148, v130, v131
	v_cvt_pk_f16_f32 v149, v132, v133
	v_cvt_pk_f16_f32 v82, v82, v83
	v_cvt_pk_f16_f32 v83, v84, v85
	v_cvt_pk_f16_f32 v84, v66, v67
	v_cvt_pk_f16_f32 v85, v68, v69
	v_permlane32_swap_b32_e32 v146, v148
	v_permlane32_swap_b32_e32 v147, v149
	v_permlane32_swap_b32_e32 v82, v84
	v_permlane32_swap_b32_e32 v83, v85
	v_permlane16_swap_b32_e32 v146, v148
	v_permlane16_swap_b32_e32 v147, v149
	v_permlane16_swap_b32_e32 v82, v84
	v_permlane16_swap_b32_e32 v83, v85
	s_nop 1
	ds_bpermute_b32 v146, v9, v146
	ds_bpermute_b32 v147, v9, v147
	ds_bpermute_b32 v148, v9, v148
	ds_bpermute_b32 v149, v9, v149
	ds_bpermute_b32 v82, v9, v82
	ds_bpermute_b32 v83, v9, v83
	ds_bpermute_b32 v84, v9, v84
	ds_bpermute_b32 v85, v9, v85
	s_waitcnt lgkmcnt(8)
	global_store_dwordx4 v[4:5], v[154:157], off
	global_store_dwordx4 v[4:5], v[90:93], off offset:256
	v_add_u32_e32 v4, 0x80, v10
	v_mad_i64_i32 v[4:5], s[4:5], v4, s94, v[2:3]
	v_lshl_add_u64 v[4:5], v[4:5], 0, v[6:7]
	v_cvt_pk_f16_f32 v126, v126, v127
	v_cvt_pk_f16_f32 v127, v128, v129
	v_cvt_pk_f16_f32 v128, v110, v111
	v_cvt_pk_f16_f32 v129, v112, v113
	v_cvt_pk_f16_f32 v62, v62, v63
	v_cvt_pk_f16_f32 v63, v64, v65
	v_cvt_pk_f16_f32 v64, v46, v47
	v_cvt_pk_f16_f32 v65, v48, v49
	v_permlane32_swap_b32_e32 v126, v128
	v_permlane32_swap_b32_e32 v127, v129
	v_permlane32_swap_b32_e32 v62, v64
	v_permlane32_swap_b32_e32 v63, v65
	v_permlane16_swap_b32_e32 v126, v128
	v_permlane16_swap_b32_e32 v127, v129
	v_permlane16_swap_b32_e32 v62, v64
	v_permlane16_swap_b32_e32 v63, v65
	s_nop 1
	ds_bpermute_b32 v126, v9, v126
	ds_bpermute_b32 v127, v9, v127
	ds_bpermute_b32 v128, v9, v128
	ds_bpermute_b32 v129, v9, v129
	ds_bpermute_b32 v62, v9, v62
	ds_bpermute_b32 v63, v9, v63
	ds_bpermute_b32 v64, v9, v64
	ds_bpermute_b32 v65, v9, v65
	s_waitcnt lgkmcnt(8)
	global_store_dwordx4 v[12:13], v[146:149], off
	global_store_dwordx4 v[12:13], v[82:85], off offset:256
	v_add_u32_e32 v12, 0x90, v10
	v_mad_i64_i32 v[12:13], s[4:5], v12, s94, v[2:3]
	v_lshl_add_u64 v[12:13], v[12:13], 0, v[6:7]
	v_cvt_pk_f16_f32 v118, v118, v119
	v_cvt_pk_f16_f32 v119, v120, v121
	v_cvt_pk_f16_f32 v120, v102, v103
	v_cvt_pk_f16_f32 v121, v104, v105
	v_cvt_pk_f16_f32 v54, v54, v55
	v_cvt_pk_f16_f32 v55, v56, v57
	v_cvt_pk_f16_f32 v56, v38, v39
	v_cvt_pk_f16_f32 v57, v40, v41
	v_permlane32_swap_b32_e32 v118, v120
	v_permlane32_swap_b32_e32 v119, v121
	v_permlane32_swap_b32_e32 v54, v56
	v_permlane32_swap_b32_e32 v55, v57
	v_permlane16_swap_b32_e32 v118, v120
	v_permlane16_swap_b32_e32 v119, v121
	v_permlane16_swap_b32_e32 v54, v56
	v_permlane16_swap_b32_e32 v55, v57
	s_nop 1
	ds_bpermute_b32 v118, v9, v118
	ds_bpermute_b32 v119, v9, v119
	ds_bpermute_b32 v120, v9, v120
	ds_bpermute_b32 v121, v9, v121
	ds_bpermute_b32 v54, v9, v54
	ds_bpermute_b32 v55, v9, v55
	ds_bpermute_b32 v56, v9, v56
	ds_bpermute_b32 v57, v9, v57
	s_waitcnt lgkmcnt(8)
	global_store_dwordx4 v[4:5], v[126:129], off
	global_store_dwordx4 v[4:5], v[62:65], off offset:256
	v_add_u32_e32 v4, 0xa0, v10
	v_mad_i64_i32 v[4:5], s[4:5], v4, s94, v[2:3]
	v_lshl_add_u64 v[4:5], v[4:5], 0, v[6:7]
	v_cvt_pk_f16_f32 v122, v122, v123
	v_cvt_pk_f16_f32 v123, v124, v125
	v_cvt_pk_f16_f32 v124, v106, v107
	v_cvt_pk_f16_f32 v125, v108, v109
	v_cvt_pk_f16_f32 v58, v58, v59
	v_cvt_pk_f16_f32 v59, v60, v61
	v_cvt_pk_f16_f32 v60, v42, v43
	v_cvt_pk_f16_f32 v61, v44, v45
	v_permlane32_swap_b32_e32 v122, v124
	v_permlane32_swap_b32_e32 v123, v125
	v_permlane32_swap_b32_e32 v58, v60
	v_permlane32_swap_b32_e32 v59, v61
	v_permlane16_swap_b32_e32 v122, v124
	v_permlane16_swap_b32_e32 v123, v125
	v_permlane16_swap_b32_e32 v58, v60
	v_permlane16_swap_b32_e32 v59, v61
	s_nop 1
	ds_bpermute_b32 v122, v9, v122
	ds_bpermute_b32 v123, v9, v123
	ds_bpermute_b32 v124, v9, v124
	ds_bpermute_b32 v125, v9, v125
	ds_bpermute_b32 v58, v9, v58
	ds_bpermute_b32 v59, v9, v59
	ds_bpermute_b32 v60, v9, v60
	ds_bpermute_b32 v61, v9, v61
	s_waitcnt lgkmcnt(8)
	global_store_dwordx4 v[12:13], v[118:121], off
	global_store_dwordx4 v[12:13], v[54:57], off offset:256
	v_add_u32_e32 v12, 0xb0, v10
	v_mad_i64_i32 v[12:13], s[4:5], v12, s94, v[2:3]
	v_lshl_add_u64 v[12:13], v[12:13], 0, v[6:7]
	v_cvt_pk_f16_f32 v114, v114, v115
	v_cvt_pk_f16_f32 v115, v116, v117
	v_cvt_pk_f16_f32 v116, v98, v99
	v_cvt_pk_f16_f32 v117, v100, v101
	v_cvt_pk_f16_f32 v50, v50, v51
	v_cvt_pk_f16_f32 v51, v52, v53
	v_cvt_pk_f16_f32 v52, v34, v35
	v_cvt_pk_f16_f32 v53, v36, v37
	v_permlane32_swap_b32_e32 v114, v116
	v_permlane32_swap_b32_e32 v115, v117
	v_permlane32_swap_b32_e32 v50, v52
	v_permlane32_swap_b32_e32 v51, v53
	v_permlane16_swap_b32_e32 v114, v116
	v_permlane16_swap_b32_e32 v115, v117
	v_permlane16_swap_b32_e32 v50, v52
	v_permlane16_swap_b32_e32 v51, v53
	s_nop 1
	ds_bpermute_b32 v114, v9, v114
	ds_bpermute_b32 v115, v9, v115
	ds_bpermute_b32 v116, v9, v116
	ds_bpermute_b32 v117, v9, v117
	ds_bpermute_b32 v50, v9, v50
	ds_bpermute_b32 v51, v9, v51
	ds_bpermute_b32 v52, v9, v52
	ds_bpermute_b32 v53, v9, v53
	s_waitcnt lgkmcnt(8)
	global_store_dwordx4 v[4:5], v[122:125], off
	global_store_dwordx4 v[4:5], v[58:61], off offset:256
	s_waitcnt lgkmcnt(0)
	global_store_dwordx4 v[12:13], v[114:117], off
	global_store_dwordx4 v[12:13], v[50:53], off offset:256
	s_nop 1
	s_mov_b64 s[4:5], 0
